# rotary epilogue pos loads hoisted to one round trip; grid-barrier acquire invalidate issued before the poll loop (7 sites)
# baseline (speedup 1.0000x reference)
; DI unsigned xb_ld(unsigned* p)              { return __hip_atomic_load(p, __ATOMIC_RELAXED, __HIP_MEMORY_SCOPE_AGENT); }
; DI unsigned xb_add(unsigned* p, unsigned v) { return __hip_atomic_fetch_add(p, v, __ATOMIC_RELAXED, __HIP_MEMORY_SCOPE_AGENT); }
; #define XB_SPIN(cond, bar) do { unsigned _sp = 0; while (cond) { __builtin_amdgcn_s_sleep(1); \
;     if ((++_sp & 255u) == 0u) { if (xb_ld(&(bar)[XB_TMO])) break; if (_sp > XB_SPIN_CAP) { atomicAdd(&(bar)[XB_TMO], 1u); break; } } } } while (0)
; DI void xcd_barrier(const XcdBarrier& b) {
;     ...
;     if (threadIdx.x == 0) {
;         unsigned* bar = b.bar;
;         __builtin_amdgcn_s_waitcnt(0);
;         unsigned nloc = b.st[0], nx = b.st[1];
;         if (nloc == 0u) { xcd_barrier_complete(bar, b.x, nloc, nx); b.st[0] = nloc; b.st[1] = nx; }
;         const unsigned old = xb_add(&bar[XB_XSUB(b.x)], 1u);
;         const unsigned gen = old / nloc;
;         if (old + 1u == (gen + 1u) * nloc) {
;             __builtin_amdgcn_fence(__ATOMIC_RELEASE, "agent");
;             asm volatile("s_waitcnt vmcnt(0)" ::: "memory");
;             const unsigned og = xb_add(&bar[XB_TOP], 1u);
;             const unsigned tg = og / nx;
;             if (og + 1u == (tg + 1u) * nx) xb_add(&bar[XB_TOPGEN], 1u);
;             else XB_SPIN(xb_ld(&bar[XB_TOPGEN]) == tg, bar);
;             __builtin_amdgcn_fence(__ATOMIC_ACQUIRE, "agent");
;             xb_add(&bar[XB_XGEN(b.x)], 1u);
;             asm volatile("s_waitcnt vmcnt(0)" ::: "memory");
;         } else {
;             XB_SPIN(xb_ld(&bar[XB_TOPGEN]) == gen, bar);
;             __builtin_amdgcn_fence(__ATOMIC_ACQUIRE, "agent");
;             asm volatile("s_waitcnt vmcnt(0)" ::: "memory");
;         }
.LBB0_60:
	s_or_b64 exec, exec, s[12:13]
	v_cvt_f32_u32_e32 v5, v3
	s_waitcnt vmcnt(0)
	v_readfirstlane_b32 s12, v4
	s_add_u32 s10, s92, 0x3500
	s_addc_u32 s11, s93, 0
	v_rcp_iflag_f32_e32 v5, v5
	v_add_u32_e32 v6, s12, v2
	v_mul_f32_e32 v4, 0x4f7ffffe, v5
	v_cvt_u32_f32_e32 v4, v4
	v_sub_u32_e32 v5, 0, v3
	v_mul_lo_u32 v2, v5, v4
	v_mul_hi_u32 v2, v4, v2
	v_add_u32_e32 v2, v4, v2
	v_mul_hi_u32 v2, v6, v2
	v_mul_lo_u32 v4, v2, v3
	v_sub_u32_e32 v4, v6, v4
	v_add_u32_e32 v5, 1, v2
	v_cmp_ge_u32_e32 vcc, v4, v3
	s_nop 1
	v_cndmask_b32_e32 v2, v2, v5, vcc
	v_sub_u32_e32 v5, v4, v3
	v_cndmask_b32_e32 v4, v4, v5, vcc
	v_add_u32_e32 v5, 1, v2
	v_cmp_ge_u32_e32 vcc, v4, v3
	v_add_u32_e32 v4, 1, v6
	s_nop 0
	v_cndmask_b32_e32 v2, v2, v5, vcc
	v_mul_lo_u32 v5, v3, v2
	v_add_u32_e32 v3, v5, v3
	v_cmp_ne_u32_e32 vcc, v4, v3
	s_and_saveexec_b64 s[12:13], vcc
	s_xor_b64 s[12:13], exec, s[12:13]
	s_cbranch_execz .LBB0_74
	s_waitcnt lgkmcnt(0)
	v_mov_b32_e32 v1, 0
	buffer_inv sc1
	global_load_dword v3, v1, s[10:11] sc1
	s_waitcnt vmcnt(0)
	v_cmp_eq_u32_e32 vcc, v3, v2
	s_and_saveexec_b64 s[14:15], vcc
	s_cbranch_execz .LBB0_73
	s_mov_b32 s27, 1
	s_mov_b64 s[16:17], 0
	s_branch .LBB0_64

; DI unsigned xb_ld(unsigned* p)              { return __hip_atomic_load(p, __ATOMIC_RELAXED, __HIP_MEMORY_SCOPE_AGENT); }
; #define XB_SPIN(cond, bar) do { unsigned _sp = 0; while (cond) { __builtin_amdgcn_s_sleep(1); \
;     if ((++_sp & 255u) == 0u) { if (xb_ld(&(bar)[XB_TMO])) break; if (_sp > XB_SPIN_CAP) { atomicAdd(&(bar)[XB_TMO], 1u); break; } } } } while (0)
; DI void xcd_barrier(const XcdBarrier& b) {
;     ...
;             XB_SPIN(xb_ld(&bar[XB_TOPGEN]) == gen, bar);
;             __builtin_amdgcn_fence(__ATOMIC_ACQUIRE, "agent");
;             asm volatile("s_waitcnt vmcnt(0)" ::: "memory");
.LBB0_73:
	s_or_b64 exec, exec, s[14:15]
	s_waitcnt vmcnt(0)
	s_waitcnt vmcnt(0)

; DI unsigned xb_ld(unsigned* p)              { return __hip_atomic_load(p, __ATOMIC_RELAXED, __HIP_MEMORY_SCOPE_AGENT); }
; DI unsigned xb_add(unsigned* p, unsigned v) { return __hip_atomic_fetch_add(p, v, __ATOMIC_RELAXED, __HIP_MEMORY_SCOPE_AGENT); }
; #define XB_SPIN(cond, bar) do { unsigned _sp = 0; while (cond) { __builtin_amdgcn_s_sleep(1); \
;     if ((++_sp & 255u) == 0u) { if (xb_ld(&(bar)[XB_TMO])) break; if (_sp > XB_SPIN_CAP) { atomicAdd(&(bar)[XB_TMO], 1u); break; } } } } while (0)
; DI void xcd_barrier(const XcdBarrier& b) {
;     ...
;     if (threadIdx.x == 0) {
;         unsigned* bar = b.bar;
;         __builtin_amdgcn_s_waitcnt(0);
;         unsigned nloc = b.st[0], nx = b.st[1];
;         if (nloc == 0u) { xcd_barrier_complete(bar, b.x, nloc, nx); b.st[0] = nloc; b.st[1] = nx; }
;         const unsigned old = xb_add(&bar[XB_XSUB(b.x)], 1u);
;         const unsigned gen = old / nloc;
;         if (old + 1u == (gen + 1u) * nloc) {
;             __builtin_amdgcn_fence(__ATOMIC_RELEASE, "agent");
;             asm volatile("s_waitcnt vmcnt(0)" ::: "memory");
;             const unsigned og = xb_add(&bar[XB_TOP], 1u);
;             const unsigned tg = og / nx;
;             if (og + 1u == (tg + 1u) * nx) xb_add(&bar[XB_TOPGEN], 1u);
;             else XB_SPIN(xb_ld(&bar[XB_TOPGEN]) == tg, bar);
;             __builtin_amdgcn_fence(__ATOMIC_ACQUIRE, "agent");
;             xb_add(&bar[XB_XGEN(b.x)], 1u);
;             asm volatile("s_waitcnt vmcnt(0)" ::: "memory");
;         } else {
;             XB_SPIN(xb_ld(&bar[XB_TOPGEN]) == gen, bar);
;             __builtin_amdgcn_fence(__ATOMIC_ACQUIRE, "agent");
;             asm volatile("s_waitcnt vmcnt(0)" ::: "memory");
;         }
.LBB0_164:
	s_or_b64 exec, exec, s[40:41]
	v_cvt_f32_u32_e32 v5, v3
	s_waitcnt vmcnt(0)
	v_readfirstlane_b32 s6, v4
	v_sub_u32_e32 v4, 0, v3
	v_rcp_iflag_f32_e32 v5, v5
	v_add_u32_e32 v6, s6, v0
	v_mul_f32_e32 v5, 0x4f7ffffe, v5
	v_cvt_u32_f32_e32 v5, v5
	v_mul_lo_u32 v0, v4, v5
	v_mul_hi_u32 v0, v5, v0
	v_add_u32_e32 v0, v5, v0
	v_mul_hi_u32 v0, v6, v0
	v_mul_lo_u32 v4, v0, v3
	v_sub_u32_e32 v4, v6, v4
	v_add_u32_e32 v5, 1, v0
	v_cmp_ge_u32_e32 vcc, v4, v3
	s_nop 1
	v_cndmask_b32_e32 v0, v0, v5, vcc
	v_sub_u32_e32 v5, v4, v3
	v_cndmask_b32_e32 v4, v4, v5, vcc
	v_add_u32_e32 v5, 1, v0
	v_cmp_ge_u32_e32 vcc, v4, v3
	v_add_u32_e32 v4, 1, v6
	s_nop 0
	v_cndmask_b32_e32 v0, v0, v5, vcc
	v_mul_lo_u32 v5, v3, v0
	v_add_u32_e32 v3, v5, v3
	v_cmp_ne_u32_e32 vcc, v4, v3
	s_and_saveexec_b64 s[8:9], vcc
	s_xor_b64 s[40:41], exec, s[8:9]
	s_cbranch_execz .LBB0_178
	v_readlane_b32 s8, v251, 2
	v_readlane_b32 s9, v251, 3
	s_waitcnt lgkmcnt(0)
	s_nop 3
	buffer_inv sc1
	global_load_dword v2, v1, s[8:9] sc1
	s_waitcnt vmcnt(0)
	v_cmp_eq_u32_e32 vcc, v2, v0
	s_and_saveexec_b64 s[42:43], vcc
	s_cbranch_execz .LBB0_177
	s_mov_b32 s6, 1
	s_mov_b64 s[46:47], 0
	s_branch .LBB0_168

; DI unsigned xb_ld(unsigned* p)              { return __hip_atomic_load(p, __ATOMIC_RELAXED, __HIP_MEMORY_SCOPE_AGENT); }
; #define XB_SPIN(cond, bar) do { unsigned _sp = 0; while (cond) { __builtin_amdgcn_s_sleep(1); \
;     if ((++_sp & 255u) == 0u) { if (xb_ld(&(bar)[XB_TMO])) break; if (_sp > XB_SPIN_CAP) { atomicAdd(&(bar)[XB_TMO], 1u); break; } } } } while (0)
; DI void xcd_barrier(const XcdBarrier& b) {
;     ...
;             XB_SPIN(xb_ld(&bar[XB_TOPGEN]) == gen, bar);
;             __builtin_amdgcn_fence(__ATOMIC_ACQUIRE, "agent");
;             asm volatile("s_waitcnt vmcnt(0)" ::: "memory");
.LBB0_177:
	s_or_b64 exec, exec, s[42:43]
	s_waitcnt vmcnt(0)
	s_waitcnt vmcnt(0)

; DI int grow_of(int lrow, int seg) { return (lrow / SEG) * S + seg * SEG + (lrow % SEG); }
;     DI void operator()(const f32x4 (&acc)[2][2][4][2], const Unit& u, int wr, int wc, int fr, int fq) const {
;         const int kc = u.pn >> 2;
;         const int lrow0 = u.pm * BM + wr * 64 + fr;
;         const int col0 = u.pn * BM + wc * 32 + 8 * fq;
;         if (kc == 5 || kc == 6) {
;             const float lg2 = log2f(1.0f - exp2f(-5.0f - (float)(u.pn & 3)));
;             const f32x4 f0 = *(const f32x4*)(invf + wc * 32 + 8 * fq), f1 = *(const f32x4*)(invf + wc * 32 + 8 * fq + 4);
; #pragma unroll
;             for (int ai = 0; ai < 2; ++ai)
; #pragma unroll
;                 for (int m = 0; m < 4; ++m) {
;                     const int lrow = lrow0 + ai * HALF + m * 16;
;                     const float ps = (float)pos[grow_of(lrow, seg)];
;                     const float pc = (float)((lrow & 63) + 1) * lg2;
;                     const float sc = (kc == 6) ? 0.0625f * exp2f(-pc) : exp2f(pc);
.LBB0_279:
	s_cmp_lg_u32 s47, 6
	s_cselect_b64 s[52:53], -1, 0
	s_and_b32 s0, s70, 3
	v_cvt_f32_ubyte0_e32 v130, s0
	v_sub_f32_e32 v130, 0xc0a00000, v130
	v_cmp_gt_f32_e32 vcc, s16, v130
	s_and_b64 s[0:1], vcc, exec
	s_cselect_b32 s0, 0xffffffc0, 0
	v_cndmask_b32_e32 v131, 0, v210, vcc
	v_add_f32_e32 v130, v130, v131
	v_exp_f32_e32 v130, v130
	v_ashrrev_i32_e32 v151, 31, v172
	v_lshrrev_b32_e32 v174, 20, v151
	v_add_u32_e32 v151, v172, v174
	v_ldexp_f32 v130, v130, s0
	v_sub_f32_e32 v130, 1.0, v130
	s_mov_b32 s0, 0x800000
	v_cmp_gt_f32_e32 vcc, s0, v130
	s_and_b64 s[0:1], vcc, exec
	s_cselect_b32 s0, 32, 0
	v_ashrrev_i32_e32 v151, 12, v151
	v_ldexp_f32 v130, v130, s0
	v_lshlrev_b32_e32 v152, 13, v151
	v_mul_i32_i24_e32 v151, 0x1000, v151
	v_log_f32_e32 v130, v130
	v_sub_u32_e32 v151, v172, v151
	v_add3_u32 v152, v151, s26, v152
	v_ashrrev_i32_e32 v153, 31, v152
	v_cndmask_b32_e32 v131, 0, v211, vcc
	v_lshl_add_u64 v[152:153], v[152:153], 2, s[80:81]
	v_sub_f32_e32 v173, v130, v131
	global_load_dwordx4 v[130:133], v[144:145], off offset:16
	global_load_dwordx4 v[134:137], v[144:145], off
	global_load_dword v151, v[152:153], off
	global_load_dword v218, v[152:153], off offset:64
	global_load_dword v219, v[152:153], off offset:128
	global_load_dword v220, v[152:153], off offset:192
	global_load_dword v221, v[152:153], off offset:512
	global_load_dword v222, v[152:153], off offset:576
	global_load_dword v223, v[152:153], off offset:640
	global_load_dword v224, v[152:153], off offset:704
	v_mul_f32_e32 v153, v173, v158
	s_mov_b64 s[42:43], -1
	s_and_b64 vcc, exec, s[52:53]
	v_cmp_gt_f32_e64 s[0:1], s16, v153
	s_cbranch_vccz .LBB0_281
	s_nop 0
	v_cndmask_b32_e64 v152, 0, v210, s[0:1]
	v_add_f32_e32 v152, v153, v152
	v_exp_f32_e32 v152, v152
	v_cndmask_b32_e64 v175, 0, v212, s[0:1]
	s_mov_b64 s[42:43], 0
	v_ldexp_f32 v152, v152, v175

; DI int grow_of(int lrow, int seg) { return (lrow / SEG) * S + seg * SEG + (lrow % SEG); }
;     DI void operator()(const f32x4 (&acc)[2][2][4][2], const Unit& u, int wr, int wc, int fr, int fq) const {
;     ...
;                 for (int m = 0; m < 4; ++m) {
;                     const int lrow = lrow0 + ai * HALF + m * 16;
;                     const float ps = (float)pos[grow_of(lrow, seg)];
;                     const float pc = (float)((lrow & 63) + 1) * lg2;
;                     const float sc = (kc == 6) ? 0.0625f * exp2f(-pc) : exp2f(pc);
;                     float o1[8], o2[8];
; #pragma unroll
;                     for (int e = 0; e < 8; ++e) {
;                         const float fe = (e < 4) ? f0[e & 3] : f1[e & 3];
;                         const float ang = ps * fe;
;                         float rev = ang * 0.15915494309189535f; rev = rev - floorf(rev);
;                         const float sn = __builtin_amdgcn_sinf(rev), cs = __builtin_amdgcn_cosf(rev);
;                         const float a = acc[ai][0][m][e >> 2][e & 3], b = acc[ai][1][m][e >> 2][e & 3];
;                         o1[e] = (a * cs - b * sn) * sc; o2[e] = (b * cs + a * sn) * sc;
;                     }
;                     bf16_t* rowp = O + (size_t)lrow * NPC + col0;
;                     u32x4 w1, w2;
;                     w1.x = cvt_pk_bf16(o1[0], o1[1]); w1.y = cvt_pk_bf16(o1[2], o1[3]); w1.z = cvt_pk_bf16(o1[4], o1[5]); w1.w = cvt_pk_bf16(o1[6], o1[7]);
;                     w2.x = cvt_pk_bf16(o2[0], o2[1]); w2.y = cvt_pk_bf16(o2[2], o2[3]); w2.z = cvt_pk_bf16(o2[4], o2[5]); w2.w = cvt_pk_bf16(o2[6], o2[7]);
;                     *(u32x4*)rowp = w1; *(u32x4*)(rowp + HALF) = w2;
.LBB0_283:
	s_waitcnt vmcnt(0)
	v_cvt_f32_i32_e32 v175, v151
	v_ashrrev_i32_e32 v151, 31, v150
	s_mov_b64 s[70:71], -1
	s_andn2_b64 vcc, exec, s[52:53]
	v_mul_f32_e32 v176, v134, v175
	v_mul_f32_e32 v178, 0.15915494, v176
	v_floor_f32_e32 v178, v178
	v_mul_f32_e32 v177, v135, v175
	v_fma_f32 v176, v176, 0.15915494, -v178
	v_sin_f32_e32 v180, v176
	v_cos_f32_e32 v182, v176
	v_mul_f32_e32 v176, 0.15915494, v177
	v_floor_f32_e32 v176, v176
	v_fma_f32 v176, v177, 0.15915494, -v176
	v_sin_f32_e32 v181, v176
	v_cos_f32_e32 v183, v176
	v_mul_f32_e32 v176, v136, v175
	v_mul_f32_e32 v177, 0.15915494, v176
	v_floor_f32_e32 v177, v177
	v_fma_f32 v176, v176, 0.15915494, -v177
	v_sin_f32_e32 v184, v176
	v_cos_f32_e32 v186, v176
	v_mul_f32_e32 v176, v137, v175
	v_mul_f32_e32 v177, 0.15915494, v176
	v_floor_f32_e32 v177, v177
	v_fma_f32 v176, v176, 0.15915494, -v177
	v_sin_f32_e32 v185, v176
	v_cos_f32_e32 v187, v176
	v_mul_f32_e32 v176, v130, v175
	v_mul_f32_e32 v177, 0.15915494, v176
	v_floor_f32_e32 v177, v177
	v_fma_f32 v176, v176, 0.15915494, -v177
	v_sin_f32_e32 v188, v176
	v_cos_f32_e32 v190, v176
	v_mul_f32_e32 v176, v131, v175
	v_mul_f32_e32 v177, 0.15915494, v176
	v_floor_f32_e32 v177, v177
	v_fma_f32 v176, v176, 0.15915494, -v177
	v_sin_f32_e32 v189, v176
	v_cos_f32_e32 v191, v176
	v_mul_f32_e32 v176, v132, v175
	v_mul_f32_e32 v177, 0.15915494, v176
	v_floor_f32_e32 v177, v177
	v_fma_f32 v176, v176, 0.15915494, -v177
	v_mul_f32_e32 v175, v133, v175
	v_sin_f32_e32 v192, v176
	v_cos_f32_e32 v194, v176
	v_mul_f32_e32 v176, 0.15915494, v175
	v_floor_f32_e32 v176, v176
	v_fma_f32 v175, v175, 0.15915494, -v176
	v_mov_b64_e32 v[176:177], s[24:25]
	v_mad_i64_i32 v[176:177], s[0:1], v172, s96, v[176:177]
	v_lshl_add_u64 v[196:197], v[150:151], 1, v[176:177]
	v_pk_mul_f32 v[176:177], v[118:119], v[180:181]
	v_pk_mul_f32 v[178:179], v[120:121], v[184:185]
	v_pk_fma_f32 v[176:177], v[126:127], v[182:183], v[176:177] neg_lo:[0,0,1] neg_hi:[0,0,1]
	v_pk_fma_f32 v[178:179], v[128:129], v[186:187], v[178:179] neg_lo:[0,0,1] neg_hi:[0,0,1]
	v_cos_f32_e32 v195, v175
	v_pk_mul_f32 v[176:177], v[176:177], v[152:153] op_sel_hi:[1,0]
	v_pk_mul_f32 v[178:179], v[178:179], v[152:153] op_sel_hi:[1,0]
	v_sin_f32_e32 v193, v175
	v_cvt_pk_bf16_f32 v176, v176, v177
	v_cvt_pk_bf16_f32 v177, v178, v179
	v_pk_mul_f32 v[178:179], v[114:115], v[188:189]
	v_pk_mul_f32 v[118:119], v[118:119], v[182:183]
	v_pk_mul_f32 v[120:121], v[120:121], v[186:187]
	v_pk_mul_f32 v[114:115], v[114:115], v[190:191]
	v_pk_fma_f32 v[118:119], v[126:127], v[180:181], v[118:119]
	v_pk_fma_f32 v[120:121], v[128:129], v[184:185], v[120:121]
	v_pk_fma_f32 v[114:115], v[122:123], v[188:189], v[114:115]
	v_pk_mul_f32 v[118:119], v[118:119], v[152:153] op_sel_hi:[1,0]
	v_pk_mul_f32 v[120:121], v[120:121], v[152:153] op_sel_hi:[1,0]
	v_pk_mul_f32 v[114:115], v[114:115], v[152:153] op_sel_hi:[1,0]
	v_cvt_pk_bf16_f32 v118, v118, v119
	v_cvt_pk_bf16_f32 v119, v120, v121
	v_cvt_pk_bf16_f32 v120, v114, v115
	v_pk_mul_f32 v[114:115], v[116:117], v[194:195]
	v_pk_mul_f32 v[198:199], v[116:117], v[192:193]
	v_pk_fma_f32 v[114:115], v[124:125], v[192:193], v[114:115]
	v_or_b32_e32 v116, 16, v172
	v_pk_mul_f32 v[114:115], v[114:115], v[152:153] op_sel_hi:[1,0]
	v_pk_fma_f32 v[178:179], v[122:123], v[190:191], v[178:179] neg_lo:[0,0,1] neg_hi:[0,0,1]
	v_cvt_pk_bf16_f32 v121, v114, v115
	v_add_u32_e32 v114, v116, v174
	v_ashrrev_i32_e32 v114, 12, v114
	v_lshlrev_b32_e32 v115, 13, v114
	v_mul_i32_i24_e32 v114, 0x1000, v114
	v_pk_fma_f32 v[198:199], v[124:125], v[194:195], v[198:199] neg_lo:[0,0,1] neg_hi:[0,0,1]
	v_sub_u32_e32 v114, v116, v114
	v_pk_mul_f32 v[178:179], v[178:179], v[152:153] op_sel_hi:[1,0]
	v_pk_mul_f32 v[198:199], v[198:199], v[152:153] op_sel_hi:[1,0]
	v_add3_u32 v114, v114, s26, v115
	v_cvt_pk_bf16_f32 v178, v178, v179
	v_cvt_pk_bf16_f32 v179, v198, v199
	v_ashrrev_i32_e32 v115, 31, v114
	global_store_dwordx4 v[196:197], v[176:179], off
	global_store_dwordx4 v[196:197], v[118:121], off offset:256
	v_lshl_add_u64 v[114:115], v[114:115], 2, s[80:81]
	v_mul_f32_e32 v115, v173, v159
	v_cndmask_b32_e64 v114, 0, 1, s[52:53]
	v_cmp_ne_u32_e64 s[42:43], 1, v114
	v_cmp_gt_f32_e64 s[0:1], s16, v115
	s_cbranch_vccnz .LBB0_285
	s_nop 0
	v_cndmask_b32_e64 v114, 0, v210, s[0:1]
	v_add_f32_e32 v114, v115, v114
	v_exp_f32_e32 v114, v114
	v_cndmask_b32_e64 v118, 0, v212, s[0:1]
	s_mov_b64 s[70:71], 0
	v_ldexp_f32 v114, v114, v118

; DI int grow_of(int lrow, int seg) { return (lrow / SEG) * S + seg * SEG + (lrow % SEG); }
;     DI void operator()(const f32x4 (&acc)[2][2][4][2], const Unit& u, int wr, int wc, int fr, int fq) const {
;     ...
;                 for (int m = 0; m < 4; ++m) {
;                     const int lrow = lrow0 + ai * HALF + m * 16;
;                     const float ps = (float)pos[grow_of(lrow, seg)];
;                     const float pc = (float)((lrow & 63) + 1) * lg2;
;                     const float sc = (kc == 6) ? 0.0625f * exp2f(-pc) : exp2f(pc);
;                     float o1[8], o2[8];
; #pragma unroll
;                     for (int e = 0; e < 8; ++e) {
;                         const float fe = (e < 4) ? f0[e & 3] : f1[e & 3];
;                         const float ang = ps * fe;
;                         float rev = ang * 0.15915494309189535f; rev = rev - floorf(rev);
;                         const float sn = __builtin_amdgcn_sinf(rev), cs = __builtin_amdgcn_cosf(rev);
;                         const float a = acc[ai][0][m][e >> 2][e & 3], b = acc[ai][1][m][e >> 2][e & 3];
;                         o1[e] = (a * cs - b * sn) * sc; o2[e] = (b * cs + a * sn) * sc;
;                     }
;                     bf16_t* rowp = O + (size_t)lrow * NPC + col0;
;                     u32x4 w1, w2;
;                     w1.x = cvt_pk_bf16(o1[0], o1[1]); w1.y = cvt_pk_bf16(o1[2], o1[3]); w1.z = cvt_pk_bf16(o1[4], o1[5]); w1.w = cvt_pk_bf16(o1[6], o1[7]);
;                     w2.x = cvt_pk_bf16(o2[0], o2[1]); w2.y = cvt_pk_bf16(o2[2], o2[3]); w2.z = cvt_pk_bf16(o2[4], o2[5]); w2.w = cvt_pk_bf16(o2[6], o2[7]);
;                     *(u32x4*)rowp = w1; *(u32x4*)(rowp + HALF) = w2;
.LBB0_287:
	v_cvt_f32_i32_e32 v117, v218
	s_mov_b64 s[52:53], -1
	s_and_b64 vcc, exec, s[42:43]
	v_mul_f32_e32 v118, v134, v117
	v_mul_f32_e32 v120, 0.15915494, v118
	v_mul_f32_e32 v119, v135, v117
	v_floor_f32_e32 v120, v120
	v_mul_f32_e32 v121, 0.15915494, v119
	v_fma_f32 v118, v118, 0.15915494, -v120
	v_sin_f32_e32 v120, v118
	v_cos_f32_e32 v122, v118
	v_floor_f32_e32 v118, v121
	v_fma_f32 v118, v119, 0.15915494, -v118
	v_sin_f32_e32 v121, v118
	v_cos_f32_e32 v123, v118
	v_mul_f32_e32 v118, v136, v117
	v_mul_f32_e32 v119, 0.15915494, v118
	v_floor_f32_e32 v119, v119
	v_fma_f32 v118, v118, 0.15915494, -v119
	v_sin_f32_e32 v124, v118
	v_cos_f32_e32 v126, v118
	v_mul_f32_e32 v118, v137, v117
	v_mul_f32_e32 v119, 0.15915494, v118
	v_floor_f32_e32 v119, v119
	v_fma_f32 v118, v118, 0.15915494, -v119
	v_sin_f32_e32 v125, v118
	v_cos_f32_e32 v127, v118
	v_mul_f32_e32 v118, v130, v117
	v_mul_f32_e32 v119, 0.15915494, v118
	v_floor_f32_e32 v119, v119
	v_fma_f32 v118, v118, 0.15915494, -v119
	v_sin_f32_e32 v128, v118
	v_cos_f32_e32 v176, v118
	v_mul_f32_e32 v118, v131, v117
	v_mul_f32_e32 v119, 0.15915494, v118
	v_floor_f32_e32 v119, v119
	v_fma_f32 v118, v118, 0.15915494, -v119
	v_sin_f32_e32 v129, v118
	v_cos_f32_e32 v177, v118
	v_mul_f32_e32 v118, v132, v117
	v_mul_f32_e32 v119, 0.15915494, v118
	v_floor_f32_e32 v119, v119
	v_fma_f32 v118, v118, 0.15915494, -v119
	v_mul_f32_e32 v117, v133, v117
	v_sin_f32_e32 v178, v118
	v_cos_f32_e32 v180, v118
	v_mul_f32_e32 v118, 0.15915494, v117
	v_floor_f32_e32 v118, v118
	v_fma_f32 v117, v117, 0.15915494, -v118
	v_mov_b64_e32 v[118:119], s[24:25]
	v_sin_f32_e32 v179, v117
	v_cos_f32_e32 v181, v117
	v_mad_i64_i32 v[116:117], s[0:1], v116, s96, v[118:119]
	v_lshl_add_u64 v[182:183], v[150:151], 1, v[116:117]
	v_pk_mul_f32 v[116:117], v[102:103], v[120:121]
	v_pk_mul_f32 v[118:119], v[104:105], v[124:125]
	v_pk_fma_f32 v[116:117], v[110:111], v[122:123], v[116:117] neg_lo:[0,0,1] neg_hi:[0,0,1]
	v_pk_fma_f32 v[118:119], v[112:113], v[126:127], v[118:119] neg_lo:[0,0,1] neg_hi:[0,0,1]
	v_pk_mul_f32 v[116:117], v[116:117], v[114:115] op_sel_hi:[1,0]
	v_pk_mul_f32 v[118:119], v[118:119], v[114:115] op_sel_hi:[1,0]
	v_cvt_pk_bf16_f32 v116, v116, v117
	v_cvt_pk_bf16_f32 v117, v118, v119
	v_pk_mul_f32 v[118:119], v[98:99], v[128:129]
	v_pk_mul_f32 v[102:103], v[102:103], v[122:123]
	v_pk_mul_f32 v[104:105], v[104:105], v[126:127]
	v_pk_mul_f32 v[98:99], v[98:99], v[176:177]
	v_pk_fma_f32 v[102:103], v[110:111], v[120:121], v[102:103]
	v_pk_fma_f32 v[104:105], v[112:113], v[124:125], v[104:105]
	v_pk_fma_f32 v[98:99], v[106:107], v[128:129], v[98:99]
	v_pk_mul_f32 v[102:103], v[102:103], v[114:115] op_sel_hi:[1,0]
	v_pk_mul_f32 v[104:105], v[104:105], v[114:115] op_sel_hi:[1,0]
	v_pk_mul_f32 v[98:99], v[98:99], v[114:115] op_sel_hi:[1,0]
	v_cvt_pk_bf16_f32 v102, v102, v103
	v_cvt_pk_bf16_f32 v103, v104, v105
	v_cvt_pk_bf16_f32 v104, v98, v99
	v_pk_mul_f32 v[98:99], v[100:101], v[180:181]
	v_pk_mul_f32 v[184:185], v[100:101], v[178:179]
	v_pk_fma_f32 v[98:99], v[108:109], v[178:179], v[98:99]
	v_or_b32_e32 v100, 32, v172
	v_pk_mul_f32 v[98:99], v[98:99], v[114:115] op_sel_hi:[1,0]
	v_pk_fma_f32 v[118:119], v[106:107], v[176:177], v[118:119] neg_lo:[0,0,1] neg_hi:[0,0,1]
	v_cvt_pk_bf16_f32 v105, v98, v99
	v_add_u32_e32 v98, v100, v174
	v_ashrrev_i32_e32 v98, 12, v98
	v_lshlrev_b32_e32 v99, 13, v98
	v_mul_i32_i24_e32 v98, 0x1000, v98
	v_pk_fma_f32 v[184:185], v[108:109], v[180:181], v[184:185] neg_lo:[0,0,1] neg_hi:[0,0,1]
	v_sub_u32_e32 v98, v100, v98
	v_pk_mul_f32 v[118:119], v[118:119], v[114:115] op_sel_hi:[1,0]
	v_pk_mul_f32 v[184:185], v[184:185], v[114:115] op_sel_hi:[1,0]
	v_add3_u32 v98, v98, s26, v99
	v_cvt_pk_bf16_f32 v118, v118, v119
	v_cvt_pk_bf16_f32 v119, v184, v185
	v_ashrrev_i32_e32 v99, 31, v98
	global_store_dwordx4 v[182:183], v[116:119], off
	global_store_dwordx4 v[182:183], v[102:105], off offset:256
	v_lshl_add_u64 v[98:99], v[98:99], 2, s[80:81]
	v_mul_f32_e32 v99, v173, v160
	v_cmp_gt_f32_e64 s[0:1], s16, v99
	s_cbranch_vccnz .LBB0_289
	s_nop 0
	v_cndmask_b32_e64 v98, 0, v210, s[0:1]
	v_add_f32_e32 v98, v99, v98
	v_exp_f32_e32 v98, v98
	v_cndmask_b32_e64 v102, 0, v212, s[0:1]
	s_mov_b64 s[52:53], 0
	v_ldexp_f32 v98, v98, v102

; DI int grow_of(int lrow, int seg) { return (lrow / SEG) * S + seg * SEG + (lrow % SEG); }
;     DI void operator()(const f32x4 (&acc)[2][2][4][2], const Unit& u, int wr, int wc, int fr, int fq) const {
;     ...
;                 for (int m = 0; m < 4; ++m) {
;                     const int lrow = lrow0 + ai * HALF + m * 16;
;                     const float ps = (float)pos[grow_of(lrow, seg)];
;                     const float pc = (float)((lrow & 63) + 1) * lg2;
;                     const float sc = (kc == 6) ? 0.0625f * exp2f(-pc) : exp2f(pc);
;                     float o1[8], o2[8];
; #pragma unroll
;                     for (int e = 0; e < 8; ++e) {
;                         const float fe = (e < 4) ? f0[e & 3] : f1[e & 3];
;                         const float ang = ps * fe;
;                         float rev = ang * 0.15915494309189535f; rev = rev - floorf(rev);
;                         const float sn = __builtin_amdgcn_sinf(rev), cs = __builtin_amdgcn_cosf(rev);
;                         const float a = acc[ai][0][m][e >> 2][e & 3], b = acc[ai][1][m][e >> 2][e & 3];
;                         o1[e] = (a * cs - b * sn) * sc; o2[e] = (b * cs + a * sn) * sc;
;                     }
;                     bf16_t* rowp = O + (size_t)lrow * NPC + col0;
;                     u32x4 w1, w2;
;                     w1.x = cvt_pk_bf16(o1[0], o1[1]); w1.y = cvt_pk_bf16(o1[2], o1[3]); w1.z = cvt_pk_bf16(o1[4], o1[5]); w1.w = cvt_pk_bf16(o1[6], o1[7]);
;                     w2.x = cvt_pk_bf16(o2[0], o2[1]); w2.y = cvt_pk_bf16(o2[2], o2[3]); w2.z = cvt_pk_bf16(o2[4], o2[5]); w2.w = cvt_pk_bf16(o2[6], o2[7]);
;                     *(u32x4*)rowp = w1; *(u32x4*)(rowp + HALF) = w2;
.LBB0_291:
	v_cvt_f32_i32_e32 v101, v219
	s_mov_b64 s[52:53], -1
	s_and_b64 vcc, exec, s[42:43]
	v_mul_f32_e32 v102, v134, v101
	v_mul_f32_e32 v104, 0.15915494, v102
	v_mul_f32_e32 v103, v135, v101
	v_floor_f32_e32 v104, v104
	v_mul_f32_e32 v105, 0.15915494, v103
	v_fma_f32 v102, v102, 0.15915494, -v104
	v_sin_f32_e32 v104, v102
	v_cos_f32_e32 v106, v102
	v_floor_f32_e32 v102, v105
	v_fma_f32 v102, v103, 0.15915494, -v102
	v_sin_f32_e32 v105, v102
	v_cos_f32_e32 v107, v102
	v_mul_f32_e32 v102, v136, v101
	v_mul_f32_e32 v103, 0.15915494, v102
	v_floor_f32_e32 v103, v103
	v_fma_f32 v102, v102, 0.15915494, -v103
	v_sin_f32_e32 v108, v102
	v_cos_f32_e32 v110, v102
	v_mul_f32_e32 v102, v137, v101
	v_mul_f32_e32 v103, 0.15915494, v102
	v_floor_f32_e32 v103, v103
	v_fma_f32 v102, v102, 0.15915494, -v103
	v_sin_f32_e32 v109, v102
	v_cos_f32_e32 v111, v102
	v_mul_f32_e32 v102, v130, v101
	v_mul_f32_e32 v103, 0.15915494, v102
	v_floor_f32_e32 v103, v103
	v_fma_f32 v102, v102, 0.15915494, -v103
	v_sin_f32_e32 v112, v102
	v_cos_f32_e32 v116, v102
	v_mul_f32_e32 v102, v131, v101
	v_mul_f32_e32 v103, 0.15915494, v102
	v_floor_f32_e32 v103, v103
	v_fma_f32 v102, v102, 0.15915494, -v103
	v_sin_f32_e32 v113, v102
	v_cos_f32_e32 v117, v102
	v_mul_f32_e32 v102, v132, v101
	v_mul_f32_e32 v103, 0.15915494, v102
	v_floor_f32_e32 v103, v103
	v_fma_f32 v102, v102, 0.15915494, -v103
	v_mul_f32_e32 v101, v133, v101
	v_sin_f32_e32 v118, v102
	v_cos_f32_e32 v120, v102
	v_mul_f32_e32 v102, 0.15915494, v101
	v_floor_f32_e32 v102, v102
	v_fma_f32 v101, v101, 0.15915494, -v102
	v_mov_b64_e32 v[102:103], s[24:25]
	v_sin_f32_e32 v119, v101
	v_cos_f32_e32 v121, v101
	v_mad_i64_i32 v[100:101], s[0:1], v100, s96, v[102:103]
	v_lshl_add_u64 v[122:123], v[150:151], 1, v[100:101]
	v_pk_mul_f32 v[100:101], v[86:87], v[104:105]
	v_pk_mul_f32 v[102:103], v[88:89], v[108:109]
	v_pk_fma_f32 v[100:101], v[94:95], v[106:107], v[100:101] neg_lo:[0,0,1] neg_hi:[0,0,1]
	v_pk_fma_f32 v[102:103], v[96:97], v[110:111], v[102:103] neg_lo:[0,0,1] neg_hi:[0,0,1]
	v_pk_mul_f32 v[100:101], v[100:101], v[98:99] op_sel_hi:[1,0]
	v_pk_mul_f32 v[102:103], v[102:103], v[98:99] op_sel_hi:[1,0]
	v_cvt_pk_bf16_f32 v100, v100, v101
	v_cvt_pk_bf16_f32 v101, v102, v103
	v_pk_mul_f32 v[102:103], v[82:83], v[112:113]
	v_pk_mul_f32 v[86:87], v[86:87], v[106:107]
	v_pk_mul_f32 v[88:89], v[88:89], v[110:111]
	v_pk_mul_f32 v[82:83], v[82:83], v[116:117]
	v_pk_fma_f32 v[86:87], v[94:95], v[104:105], v[86:87]
	v_pk_fma_f32 v[88:89], v[96:97], v[108:109], v[88:89]
	v_pk_fma_f32 v[82:83], v[90:91], v[112:113], v[82:83]
	v_pk_mul_f32 v[86:87], v[86:87], v[98:99] op_sel_hi:[1,0]
	v_pk_mul_f32 v[88:89], v[88:89], v[98:99] op_sel_hi:[1,0]
	v_pk_mul_f32 v[82:83], v[82:83], v[98:99] op_sel_hi:[1,0]
	v_cvt_pk_bf16_f32 v86, v86, v87
	v_cvt_pk_bf16_f32 v87, v88, v89
	v_cvt_pk_bf16_f32 v88, v82, v83
	v_pk_mul_f32 v[82:83], v[84:85], v[120:121]
	v_pk_mul_f32 v[124:125], v[84:85], v[118:119]
	v_pk_fma_f32 v[82:83], v[92:93], v[118:119], v[82:83]
	v_or_b32_e32 v84, 48, v172
	v_pk_mul_f32 v[82:83], v[82:83], v[98:99] op_sel_hi:[1,0]
	v_pk_fma_f32 v[102:103], v[90:91], v[116:117], v[102:103] neg_lo:[0,0,1] neg_hi:[0,0,1]
	v_cvt_pk_bf16_f32 v89, v82, v83
	v_add_u32_e32 v82, v84, v174
	v_ashrrev_i32_e32 v82, 12, v82
	v_lshlrev_b32_e32 v83, 13, v82
	v_mul_i32_i24_e32 v82, 0x1000, v82
	v_pk_fma_f32 v[124:125], v[92:93], v[120:121], v[124:125] neg_lo:[0,0,1] neg_hi:[0,0,1]
	v_sub_u32_e32 v82, v84, v82
	v_pk_mul_f32 v[102:103], v[102:103], v[98:99] op_sel_hi:[1,0]
	v_pk_mul_f32 v[124:125], v[124:125], v[98:99] op_sel_hi:[1,0]
	v_add3_u32 v82, v82, s26, v83
	v_cvt_pk_bf16_f32 v102, v102, v103
	v_cvt_pk_bf16_f32 v103, v124, v125
	v_ashrrev_i32_e32 v83, 31, v82
	global_store_dwordx4 v[122:123], v[100:103], off
	global_store_dwordx4 v[122:123], v[86:89], off offset:256
	v_lshl_add_u64 v[82:83], v[82:83], 2, s[80:81]
	v_mul_f32_e32 v83, v173, v161
	v_cmp_gt_f32_e64 s[0:1], s16, v83
	s_cbranch_vccnz .LBB0_293
	s_nop 0
	v_cndmask_b32_e64 v82, 0, v210, s[0:1]
	v_add_f32_e32 v82, v83, v82
	v_exp_f32_e32 v82, v82
	v_cndmask_b32_e64 v86, 0, v212, s[0:1]
	s_mov_b64 s[52:53], 0
	v_ldexp_f32 v82, v82, v86

; DI int grow_of(int lrow, int seg) { return (lrow / SEG) * S + seg * SEG + (lrow % SEG); }
;     DI void operator()(const f32x4 (&acc)[2][2][4][2], const Unit& u, int wr, int wc, int fr, int fq) const {
;     ...
;                 for (int m = 0; m < 4; ++m) {
;                     const int lrow = lrow0 + ai * HALF + m * 16;
;                     const float ps = (float)pos[grow_of(lrow, seg)];
;                     const float pc = (float)((lrow & 63) + 1) * lg2;
;                     const float sc = (kc == 6) ? 0.0625f * exp2f(-pc) : exp2f(pc);
;                     float o1[8], o2[8];
; #pragma unroll
;                     for (int e = 0; e < 8; ++e) {
;                         const float fe = (e < 4) ? f0[e & 3] : f1[e & 3];
;                         const float ang = ps * fe;
;                         float rev = ang * 0.15915494309189535f; rev = rev - floorf(rev);
;                         const float sn = __builtin_amdgcn_sinf(rev), cs = __builtin_amdgcn_cosf(rev);
;                         const float a = acc[ai][0][m][e >> 2][e & 3], b = acc[ai][1][m][e >> 2][e & 3];
;                         o1[e] = (a * cs - b * sn) * sc; o2[e] = (b * cs + a * sn) * sc;
;                     }
;                     bf16_t* rowp = O + (size_t)lrow * NPC + col0;
;                     u32x4 w1, w2;
;                     w1.x = cvt_pk_bf16(o1[0], o1[1]); w1.y = cvt_pk_bf16(o1[2], o1[3]); w1.z = cvt_pk_bf16(o1[4], o1[5]); w1.w = cvt_pk_bf16(o1[6], o1[7]);
;                     w2.x = cvt_pk_bf16(o2[0], o2[1]); w2.y = cvt_pk_bf16(o2[2], o2[3]); w2.z = cvt_pk_bf16(o2[4], o2[5]); w2.w = cvt_pk_bf16(o2[6], o2[7]);
;                     *(u32x4*)rowp = w1; *(u32x4*)(rowp + HALF) = w2;
.LBB0_295:
	v_cvt_f32_i32_e32 v85, v220
	s_and_b64 vcc, exec, s[42:43]
	v_mul_f32_e32 v86, v134, v85
	v_mul_f32_e32 v88, 0.15915494, v86
	v_mul_f32_e32 v87, v135, v85
	v_floor_f32_e32 v88, v88
	v_mul_f32_e32 v89, 0.15915494, v87
	v_fma_f32 v86, v86, 0.15915494, -v88
	v_sin_f32_e32 v88, v86
	v_cos_f32_e32 v90, v86
	v_floor_f32_e32 v86, v89
	v_fma_f32 v86, v87, 0.15915494, -v86
	v_sin_f32_e32 v89, v86
	v_cos_f32_e32 v91, v86
	v_mul_f32_e32 v86, v136, v85
	v_mul_f32_e32 v87, 0.15915494, v86
	v_floor_f32_e32 v87, v87
	v_fma_f32 v86, v86, 0.15915494, -v87
	v_sin_f32_e32 v92, v86
	v_cos_f32_e32 v94, v86
	v_mul_f32_e32 v86, v137, v85
	v_mul_f32_e32 v87, 0.15915494, v86
	v_floor_f32_e32 v87, v87
	v_fma_f32 v86, v86, 0.15915494, -v87
	v_sin_f32_e32 v93, v86
	v_cos_f32_e32 v95, v86
	v_mul_f32_e32 v86, v130, v85
	v_mul_f32_e32 v87, 0.15915494, v86
	v_floor_f32_e32 v87, v87
	v_fma_f32 v86, v86, 0.15915494, -v87
	v_sin_f32_e32 v96, v86
	v_cos_f32_e32 v100, v86
	v_mul_f32_e32 v86, v131, v85
	v_mul_f32_e32 v87, 0.15915494, v86
	v_floor_f32_e32 v87, v87
	v_fma_f32 v86, v86, 0.15915494, -v87
	v_sin_f32_e32 v97, v86
	v_cos_f32_e32 v101, v86
	v_mul_f32_e32 v86, v132, v85
	v_mul_f32_e32 v87, 0.15915494, v86
	v_floor_f32_e32 v87, v87
	v_fma_f32 v86, v86, 0.15915494, -v87
	v_mul_f32_e32 v85, v133, v85
	v_sin_f32_e32 v102, v86
	v_cos_f32_e32 v104, v86
	v_mul_f32_e32 v86, 0.15915494, v85
	v_floor_f32_e32 v86, v86
	v_fma_f32 v85, v85, 0.15915494, -v86
	v_mov_b64_e32 v[86:87], s[24:25]
	v_sin_f32_e32 v103, v85
	v_cos_f32_e32 v105, v85
	v_mad_i64_i32 v[84:85], s[0:1], v84, s96, v[86:87]
	v_lshl_add_u64 v[106:107], v[150:151], 1, v[84:85]
	v_pk_mul_f32 v[84:85], v[70:71], v[88:89]
	v_pk_mul_f32 v[86:87], v[72:73], v[92:93]
	v_pk_fma_f32 v[84:85], v[78:79], v[90:91], v[84:85] neg_lo:[0,0,1] neg_hi:[0,0,1]
	v_pk_fma_f32 v[86:87], v[80:81], v[94:95], v[86:87] neg_lo:[0,0,1] neg_hi:[0,0,1]
	v_pk_mul_f32 v[84:85], v[84:85], v[82:83] op_sel_hi:[1,0]
	v_pk_mul_f32 v[86:87], v[86:87], v[82:83] op_sel_hi:[1,0]
	v_cvt_pk_bf16_f32 v84, v84, v85
	v_cvt_pk_bf16_f32 v85, v86, v87
	v_pk_mul_f32 v[86:87], v[66:67], v[96:97]
	v_pk_mul_f32 v[70:71], v[70:71], v[90:91]
	v_pk_mul_f32 v[72:73], v[72:73], v[94:95]
	v_pk_mul_f32 v[66:67], v[66:67], v[100:101]
	v_pk_fma_f32 v[70:71], v[78:79], v[88:89], v[70:71]
	v_pk_fma_f32 v[72:73], v[80:81], v[92:93], v[72:73]
	v_pk_fma_f32 v[66:67], v[74:75], v[96:97], v[66:67]
	v_pk_mul_f32 v[70:71], v[70:71], v[82:83] op_sel_hi:[1,0]
	v_pk_mul_f32 v[72:73], v[72:73], v[82:83] op_sel_hi:[1,0]
	v_pk_mul_f32 v[66:67], v[66:67], v[82:83] op_sel_hi:[1,0]
	v_cvt_pk_bf16_f32 v70, v70, v71
	v_cvt_pk_bf16_f32 v71, v72, v73
	v_cvt_pk_bf16_f32 v72, v66, v67
	v_pk_mul_f32 v[66:67], v[68:69], v[104:105]
	v_pk_mul_f32 v[108:109], v[68:69], v[102:103]
	v_pk_fma_f32 v[66:67], v[76:77], v[102:103], v[66:67]
	v_pk_fma_f32 v[86:87], v[74:75], v[100:101], v[86:87] neg_lo:[0,0,1] neg_hi:[0,0,1]
	v_pk_mul_f32 v[66:67], v[66:67], v[82:83] op_sel_hi:[1,0]
	v_pk_fma_f32 v[108:109], v[76:77], v[104:105], v[108:109] neg_lo:[0,0,1] neg_hi:[0,0,1]
	v_cvt_pk_bf16_f32 v73, v66, v67
	v_add_u32_e32 v67, 0x80, v172
	v_ashrrev_i32_e32 v66, 31, v67
	v_lshrrev_b32_e32 v66, 20, v66
	v_add_u32_e32 v66, v67, v66
	v_ashrrev_i32_e32 v66, 12, v66
	v_lshlrev_b32_e32 v68, 13, v66
	v_mul_i32_i24_e32 v66, 0x1000, v66
	v_sub_u32_e32 v66, v67, v66
	v_pk_mul_f32 v[86:87], v[86:87], v[82:83] op_sel_hi:[1,0]
	v_pk_mul_f32 v[108:109], v[108:109], v[82:83] op_sel_hi:[1,0]
	v_add3_u32 v68, v66, s26, v68
	v_cvt_pk_bf16_f32 v86, v86, v87
	v_cvt_pk_bf16_f32 v87, v108, v109
	v_ashrrev_i32_e32 v69, 31, v68
	global_store_dwordx4 v[106:107], v[84:87], off
	global_store_dwordx4 v[106:107], v[70:73], off offset:256
	v_lshl_add_u64 v[68:69], v[68:69], 2, s[80:81]
	s_mov_b64 s[0:1], -1
	s_cbranch_vccnz .LBB0_297
	v_cmp_gt_f32_e32 vcc, s16, v153
	s_mov_b64 s[0:1], 0
	s_nop 0
	v_cndmask_b32_e32 v69, 0, v210, vcc
	v_add_f32_e32 v69, v153, v69
	v_exp_f32_e32 v69, v69
	v_cndmask_b32_e32 v66, 0, v212, vcc
	v_ldexp_f32 v66, v69, v66

; DI int grow_of(int lrow, int seg) { return (lrow / SEG) * S + seg * SEG + (lrow % SEG); }
;     DI void operator()(const f32x4 (&acc)[2][2][4][2], const Unit& u, int wr, int wc, int fr, int fq) const {
;     ...
;                 for (int m = 0; m < 4; ++m) {
;                     const int lrow = lrow0 + ai * HALF + m * 16;
;                     const float ps = (float)pos[grow_of(lrow, seg)];
;                     const float pc = (float)((lrow & 63) + 1) * lg2;
;                     const float sc = (kc == 6) ? 0.0625f * exp2f(-pc) : exp2f(pc);
;                     float o1[8], o2[8];
; #pragma unroll
;                     for (int e = 0; e < 8; ++e) {
;                         const float fe = (e < 4) ? f0[e & 3] : f1[e & 3];
;                         const float ang = ps * fe;
;                         float rev = ang * 0.15915494309189535f; rev = rev - floorf(rev);
;                         const float sn = __builtin_amdgcn_sinf(rev), cs = __builtin_amdgcn_cosf(rev);
;                         const float a = acc[ai][0][m][e >> 2][e & 3], b = acc[ai][1][m][e >> 2][e & 3];
;                         o1[e] = (a * cs - b * sn) * sc; o2[e] = (b * cs + a * sn) * sc;
;                     }
;                     bf16_t* rowp = O + (size_t)lrow * NPC + col0;
;                     u32x4 w1, w2;
;                     w1.x = cvt_pk_bf16(o1[0], o1[1]); w1.y = cvt_pk_bf16(o1[2], o1[3]); w1.z = cvt_pk_bf16(o1[4], o1[5]); w1.w = cvt_pk_bf16(o1[6], o1[7]);
;                     w2.x = cvt_pk_bf16(o2[0], o2[1]); w2.y = cvt_pk_bf16(o2[2], o2[3]); w2.z = cvt_pk_bf16(o2[4], o2[5]); w2.w = cvt_pk_bf16(o2[6], o2[7]);
;                     *(u32x4*)rowp = w1; *(u32x4*)(rowp + HALF) = w2;
.LBB0_299:
	v_cvt_f32_i32_e32 v68, v221
	s_and_b64 vcc, exec, s[42:43]
	v_mul_f32_e32 v69, v134, v68
	v_mul_f32_e32 v71, 0.15915494, v69
	v_mul_f32_e32 v70, v135, v68
	v_floor_f32_e32 v71, v71
	v_mul_f32_e32 v73, 0.15915494, v70
	v_fma_f32 v69, v69, 0.15915494, -v71
	v_sin_f32_e32 v72, v69
	v_cos_f32_e32 v74, v69
	v_floor_f32_e32 v69, v73
	v_fma_f32 v69, v70, 0.15915494, -v69
	v_sin_f32_e32 v73, v69
	v_cos_f32_e32 v75, v69
	v_mul_f32_e32 v69, v136, v68
	v_mul_f32_e32 v70, 0.15915494, v69
	v_floor_f32_e32 v70, v70
	v_fma_f32 v69, v69, 0.15915494, -v70
	v_sin_f32_e32 v76, v69
	v_cos_f32_e32 v78, v69
	v_mul_f32_e32 v69, v137, v68
	v_mul_f32_e32 v70, 0.15915494, v69
	v_floor_f32_e32 v70, v70
	v_fma_f32 v69, v69, 0.15915494, -v70
	v_sin_f32_e32 v77, v69
	v_cos_f32_e32 v79, v69
	v_mul_f32_e32 v69, v130, v68
	v_mul_f32_e32 v70, 0.15915494, v69
	v_floor_f32_e32 v70, v70
	v_fma_f32 v69, v69, 0.15915494, -v70
	v_sin_f32_e32 v80, v69
	v_cos_f32_e32 v84, v69
	v_mul_f32_e32 v69, v131, v68
	v_mul_f32_e32 v70, 0.15915494, v69
	v_floor_f32_e32 v70, v70
	v_fma_f32 v69, v69, 0.15915494, -v70
	v_sin_f32_e32 v81, v69
	v_cos_f32_e32 v85, v69
	v_mul_f32_e32 v69, v132, v68
	v_mul_f32_e32 v70, 0.15915494, v69
	v_floor_f32_e32 v70, v70
	v_fma_f32 v69, v69, 0.15915494, -v70
	v_mul_f32_e32 v68, v133, v68
	v_sin_f32_e32 v86, v69
	v_cos_f32_e32 v88, v69
	v_mul_f32_e32 v69, 0.15915494, v68
	v_floor_f32_e32 v69, v69
	v_fma_f32 v68, v68, 0.15915494, -v69
	v_sin_f32_e32 v87, v68
	v_cos_f32_e32 v89, v68
	v_mov_b64_e32 v[68:69], s[24:25]
	v_mad_i64_i32 v[68:69], s[0:1], v67, s96, v[68:69]
	v_lshl_add_u64 v[90:91], v[150:151], 1, v[68:69]
	v_pk_mul_f32 v[68:69], v[54:55], v[72:73]
	v_pk_mul_f32 v[70:71], v[56:57], v[76:77]
	v_pk_fma_f32 v[68:69], v[62:63], v[74:75], v[68:69] neg_lo:[0,0,1] neg_hi:[0,0,1]
	v_pk_fma_f32 v[70:71], v[64:65], v[78:79], v[70:71] neg_lo:[0,0,1] neg_hi:[0,0,1]
	v_pk_mul_f32 v[68:69], v[68:69], v[66:67] op_sel_hi:[1,0]
	v_pk_mul_f32 v[70:71], v[70:71], v[66:67] op_sel_hi:[1,0]
	v_cvt_pk_bf16_f32 v68, v68, v69
	v_cvt_pk_bf16_f32 v69, v70, v71
	v_pk_mul_f32 v[70:71], v[50:51], v[80:81]
	v_pk_mul_f32 v[54:55], v[54:55], v[74:75]
	v_pk_mul_f32 v[56:57], v[56:57], v[78:79]
	v_pk_mul_f32 v[50:51], v[50:51], v[84:85]
	v_pk_fma_f32 v[54:55], v[62:63], v[72:73], v[54:55]
	v_pk_fma_f32 v[56:57], v[64:65], v[76:77], v[56:57]
	v_pk_fma_f32 v[50:51], v[58:59], v[80:81], v[50:51]
	v_pk_mul_f32 v[54:55], v[54:55], v[66:67] op_sel_hi:[1,0]
	v_pk_mul_f32 v[56:57], v[56:57], v[66:67] op_sel_hi:[1,0]
	v_pk_mul_f32 v[50:51], v[50:51], v[66:67] op_sel_hi:[1,0]
	v_cvt_pk_bf16_f32 v54, v54, v55
	v_cvt_pk_bf16_f32 v55, v56, v57
	v_cvt_pk_bf16_f32 v56, v50, v51
	v_pk_mul_f32 v[50:51], v[52:53], v[88:89]
	v_pk_mul_f32 v[92:93], v[52:53], v[86:87]
	v_pk_fma_f32 v[50:51], v[60:61], v[86:87], v[50:51]
	v_pk_fma_f32 v[70:71], v[58:59], v[84:85], v[70:71] neg_lo:[0,0,1] neg_hi:[0,0,1]
	v_pk_mul_f32 v[50:51], v[50:51], v[66:67] op_sel_hi:[1,0]
	v_pk_fma_f32 v[92:93], v[60:61], v[88:89], v[92:93] neg_lo:[0,0,1] neg_hi:[0,0,1]
	v_cvt_pk_bf16_f32 v57, v50, v51
	v_add_u32_e32 v51, 0x90, v172
	v_ashrrev_i32_e32 v50, 31, v51
	v_lshrrev_b32_e32 v50, 20, v50
	v_add_u32_e32 v50, v51, v50
	v_ashrrev_i32_e32 v50, 12, v50
	v_lshlrev_b32_e32 v52, 13, v50
	v_mul_i32_i24_e32 v50, 0x1000, v50
	v_sub_u32_e32 v50, v51, v50
	v_pk_mul_f32 v[70:71], v[70:71], v[66:67] op_sel_hi:[1,0]
	v_pk_mul_f32 v[92:93], v[92:93], v[66:67] op_sel_hi:[1,0]
	v_add3_u32 v52, v50, s26, v52
	v_cvt_pk_bf16_f32 v70, v70, v71
	v_cvt_pk_bf16_f32 v71, v92, v93
	v_ashrrev_i32_e32 v53, 31, v52
	global_store_dwordx4 v[90:91], v[68:71], off
	global_store_dwordx4 v[90:91], v[54:57], off offset:256
	v_lshl_add_u64 v[52:53], v[52:53], 2, s[80:81]
	s_mov_b64 s[0:1], -1
	s_cbranch_vccnz .LBB0_301
	v_cmp_gt_f32_e32 vcc, s16, v115
	s_mov_b64 s[0:1], 0
	s_nop 0
	v_cndmask_b32_e32 v53, 0, v210, vcc
	v_add_f32_e32 v53, v115, v53
	v_exp_f32_e32 v53, v53
	v_cndmask_b32_e32 v50, 0, v212, vcc
	v_ldexp_f32 v50, v53, v50

; DI int grow_of(int lrow, int seg) { return (lrow / SEG) * S + seg * SEG + (lrow % SEG); }
;     DI void operator()(const f32x4 (&acc)[2][2][4][2], const Unit& u, int wr, int wc, int fr, int fq) const {
;     ...
;                 for (int m = 0; m < 4; ++m) {
;                     const int lrow = lrow0 + ai * HALF + m * 16;
;                     const float ps = (float)pos[grow_of(lrow, seg)];
;                     const float pc = (float)((lrow & 63) + 1) * lg2;
;                     const float sc = (kc == 6) ? 0.0625f * exp2f(-pc) : exp2f(pc);
;                     float o1[8], o2[8];
; #pragma unroll
;                     for (int e = 0; e < 8; ++e) {
;                         const float fe = (e < 4) ? f0[e & 3] : f1[e & 3];
;                         const float ang = ps * fe;
;                         float rev = ang * 0.15915494309189535f; rev = rev - floorf(rev);
;                         const float sn = __builtin_amdgcn_sinf(rev), cs = __builtin_amdgcn_cosf(rev);
;                         const float a = acc[ai][0][m][e >> 2][e & 3], b = acc[ai][1][m][e >> 2][e & 3];
;                         o1[e] = (a * cs - b * sn) * sc; o2[e] = (b * cs + a * sn) * sc;
;                     }
;                     bf16_t* rowp = O + (size_t)lrow * NPC + col0;
;                     u32x4 w1, w2;
;                     w1.x = cvt_pk_bf16(o1[0], o1[1]); w1.y = cvt_pk_bf16(o1[2], o1[3]); w1.z = cvt_pk_bf16(o1[4], o1[5]); w1.w = cvt_pk_bf16(o1[6], o1[7]);
;                     w2.x = cvt_pk_bf16(o2[0], o2[1]); w2.y = cvt_pk_bf16(o2[2], o2[3]); w2.z = cvt_pk_bf16(o2[4], o2[5]); w2.w = cvt_pk_bf16(o2[6], o2[7]);
;                     *(u32x4*)rowp = w1; *(u32x4*)(rowp + HALF) = w2;
.LBB0_303:
	v_cvt_f32_i32_e32 v52, v222
	s_and_b64 vcc, exec, s[42:43]
	v_mul_f32_e32 v53, v134, v52
	v_mul_f32_e32 v55, 0.15915494, v53
	v_mul_f32_e32 v54, v135, v52
	v_floor_f32_e32 v55, v55
	v_mul_f32_e32 v57, 0.15915494, v54
	v_fma_f32 v53, v53, 0.15915494, -v55
	v_sin_f32_e32 v56, v53
	v_cos_f32_e32 v58, v53
	v_floor_f32_e32 v53, v57
	v_fma_f32 v53, v54, 0.15915494, -v53
	v_sin_f32_e32 v57, v53
	v_cos_f32_e32 v59, v53
	v_mul_f32_e32 v53, v136, v52
	v_mul_f32_e32 v54, 0.15915494, v53
	v_floor_f32_e32 v54, v54
	v_fma_f32 v53, v53, 0.15915494, -v54
	v_sin_f32_e32 v60, v53
	v_cos_f32_e32 v62, v53
	v_mul_f32_e32 v53, v137, v52
	v_mul_f32_e32 v54, 0.15915494, v53
	v_floor_f32_e32 v54, v54
	v_fma_f32 v53, v53, 0.15915494, -v54
	v_sin_f32_e32 v61, v53
	v_cos_f32_e32 v63, v53
	v_mul_f32_e32 v53, v130, v52
	v_mul_f32_e32 v54, 0.15915494, v53
	v_floor_f32_e32 v54, v54
	v_fma_f32 v53, v53, 0.15915494, -v54
	v_sin_f32_e32 v64, v53
	v_cos_f32_e32 v66, v53
	v_mul_f32_e32 v53, v131, v52
	v_mul_f32_e32 v54, 0.15915494, v53
	v_floor_f32_e32 v54, v54
	v_fma_f32 v53, v53, 0.15915494, -v54
	v_sin_f32_e32 v65, v53
	v_cos_f32_e32 v67, v53
	v_mul_f32_e32 v53, v132, v52
	v_mul_f32_e32 v54, 0.15915494, v53
	v_floor_f32_e32 v54, v54
	v_fma_f32 v53, v53, 0.15915494, -v54
	v_mul_f32_e32 v52, v133, v52
	v_sin_f32_e32 v68, v53
	v_cos_f32_e32 v70, v53
	v_mul_f32_e32 v53, 0.15915494, v52
	v_floor_f32_e32 v53, v53
	v_fma_f32 v52, v52, 0.15915494, -v53
	v_sin_f32_e32 v69, v52
	v_cos_f32_e32 v71, v52
	v_mov_b64_e32 v[52:53], s[24:25]
	v_mad_i64_i32 v[52:53], s[0:1], v51, s96, v[52:53]
	v_lshl_add_u64 v[72:73], v[150:151], 1, v[52:53]
	v_pk_mul_f32 v[52:53], v[38:39], v[56:57]
	v_pk_mul_f32 v[54:55], v[40:41], v[60:61]
	v_pk_fma_f32 v[52:53], v[46:47], v[58:59], v[52:53] neg_lo:[0,0,1] neg_hi:[0,0,1]
	v_pk_fma_f32 v[54:55], v[48:49], v[62:63], v[54:55] neg_lo:[0,0,1] neg_hi:[0,0,1]
	v_pk_mul_f32 v[52:53], v[52:53], v[50:51] op_sel_hi:[1,0]
	v_pk_mul_f32 v[54:55], v[54:55], v[50:51] op_sel_hi:[1,0]
	v_cvt_pk_bf16_f32 v52, v52, v53
	v_cvt_pk_bf16_f32 v53, v54, v55
	v_pk_mul_f32 v[54:55], v[34:35], v[64:65]
	v_pk_mul_f32 v[38:39], v[38:39], v[58:59]
	v_pk_mul_f32 v[40:41], v[40:41], v[62:63]
	v_pk_mul_f32 v[34:35], v[34:35], v[66:67]
	v_pk_fma_f32 v[38:39], v[46:47], v[56:57], v[38:39]
	v_pk_fma_f32 v[40:41], v[48:49], v[60:61], v[40:41]
	v_pk_fma_f32 v[34:35], v[42:43], v[64:65], v[34:35]
	v_pk_mul_f32 v[38:39], v[38:39], v[50:51] op_sel_hi:[1,0]
	v_pk_mul_f32 v[40:41], v[40:41], v[50:51] op_sel_hi:[1,0]
	v_pk_mul_f32 v[34:35], v[34:35], v[50:51] op_sel_hi:[1,0]
	v_cvt_pk_bf16_f32 v38, v38, v39
	v_cvt_pk_bf16_f32 v39, v40, v41
	v_cvt_pk_bf16_f32 v40, v34, v35
	v_pk_mul_f32 v[34:35], v[36:37], v[70:71]
	v_pk_mul_f32 v[74:75], v[36:37], v[68:69]
	v_pk_fma_f32 v[34:35], v[44:45], v[68:69], v[34:35]
	v_pk_fma_f32 v[54:55], v[42:43], v[66:67], v[54:55] neg_lo:[0,0,1] neg_hi:[0,0,1]
	v_pk_mul_f32 v[34:35], v[34:35], v[50:51] op_sel_hi:[1,0]
	v_pk_fma_f32 v[74:75], v[44:45], v[70:71], v[74:75] neg_lo:[0,0,1] neg_hi:[0,0,1]
	v_cvt_pk_bf16_f32 v41, v34, v35
	v_add_u32_e32 v35, 0xa0, v172
	v_ashrrev_i32_e32 v34, 31, v35
	v_lshrrev_b32_e32 v34, 20, v34
	v_add_u32_e32 v34, v35, v34
	v_ashrrev_i32_e32 v34, 12, v34
	v_lshlrev_b32_e32 v36, 13, v34
	v_mul_i32_i24_e32 v34, 0x1000, v34
	v_sub_u32_e32 v34, v35, v34
	v_pk_mul_f32 v[54:55], v[54:55], v[50:51] op_sel_hi:[1,0]
	v_pk_mul_f32 v[74:75], v[74:75], v[50:51] op_sel_hi:[1,0]
	v_add3_u32 v36, v34, s26, v36
	v_cvt_pk_bf16_f32 v54, v54, v55
	v_cvt_pk_bf16_f32 v55, v74, v75
	v_ashrrev_i32_e32 v37, 31, v36
	global_store_dwordx4 v[72:73], v[52:55], off
	global_store_dwordx4 v[72:73], v[38:41], off offset:256
	v_lshl_add_u64 v[36:37], v[36:37], 2, s[80:81]
	s_mov_b64 s[0:1], -1
	s_cbranch_vccnz .LBB0_305
	v_cmp_gt_f32_e32 vcc, s16, v99
	s_mov_b64 s[0:1], 0
	s_nop 0
	v_cndmask_b32_e32 v37, 0, v210, vcc
	v_add_f32_e32 v37, v99, v37
	v_exp_f32_e32 v37, v37
	v_cndmask_b32_e32 v34, 0, v212, vcc
	v_ldexp_f32 v34, v37, v34

; DI int grow_of(int lrow, int seg) { return (lrow / SEG) * S + seg * SEG + (lrow % SEG); }
;     DI void operator()(const f32x4 (&acc)[2][2][4][2], const Unit& u, int wr, int wc, int fr, int fq) const {
;     ...
;                 for (int m = 0; m < 4; ++m) {
;                     const int lrow = lrow0 + ai * HALF + m * 16;
;                     const float ps = (float)pos[grow_of(lrow, seg)];
;                     const float pc = (float)((lrow & 63) + 1) * lg2;
;                     const float sc = (kc == 6) ? 0.0625f * exp2f(-pc) : exp2f(pc);
;                     float o1[8], o2[8];
; #pragma unroll
;                     for (int e = 0; e < 8; ++e) {
;                         const float fe = (e < 4) ? f0[e & 3] : f1[e & 3];
;                         const float ang = ps * fe;
;                         float rev = ang * 0.15915494309189535f; rev = rev - floorf(rev);
;                         const float sn = __builtin_amdgcn_sinf(rev), cs = __builtin_amdgcn_cosf(rev);
;                         const float a = acc[ai][0][m][e >> 2][e & 3], b = acc[ai][1][m][e >> 2][e & 3];
;                         o1[e] = (a * cs - b * sn) * sc; o2[e] = (b * cs + a * sn) * sc;
;                     }
;                     bf16_t* rowp = O + (size_t)lrow * NPC + col0;
;                     u32x4 w1, w2;
;                     w1.x = cvt_pk_bf16(o1[0], o1[1]); w1.y = cvt_pk_bf16(o1[2], o1[3]); w1.z = cvt_pk_bf16(o1[4], o1[5]); w1.w = cvt_pk_bf16(o1[6], o1[7]);
;                     w2.x = cvt_pk_bf16(o2[0], o2[1]); w2.y = cvt_pk_bf16(o2[2], o2[3]); w2.z = cvt_pk_bf16(o2[4], o2[5]); w2.w = cvt_pk_bf16(o2[6], o2[7]);
;                     *(u32x4*)rowp = w1; *(u32x4*)(rowp + HALF) = w2;
.LBB0_307:
	v_cvt_f32_i32_e32 v36, v223
	s_and_b64 vcc, exec, s[42:43]
	v_mul_f32_e32 v37, v134, v36
	v_mul_f32_e32 v39, 0.15915494, v37
	v_mul_f32_e32 v38, v135, v36
	v_floor_f32_e32 v39, v39
	v_mul_f32_e32 v41, 0.15915494, v38
	v_fma_f32 v37, v37, 0.15915494, -v39
	v_sin_f32_e32 v40, v37
	v_cos_f32_e32 v42, v37
	v_floor_f32_e32 v37, v41
	v_fma_f32 v37, v38, 0.15915494, -v37
	v_sin_f32_e32 v41, v37
	v_cos_f32_e32 v43, v37
	v_mul_f32_e32 v37, v136, v36
	v_mul_f32_e32 v38, 0.15915494, v37
	v_floor_f32_e32 v38, v38
	v_fma_f32 v37, v37, 0.15915494, -v38
	v_sin_f32_e32 v44, v37
	v_cos_f32_e32 v46, v37
	v_mul_f32_e32 v37, v137, v36
	v_mul_f32_e32 v38, 0.15915494, v37
	v_floor_f32_e32 v38, v38
	v_fma_f32 v37, v37, 0.15915494, -v38
	v_sin_f32_e32 v45, v37
	v_cos_f32_e32 v47, v37
	v_mul_f32_e32 v37, v130, v36
	v_mul_f32_e32 v38, 0.15915494, v37
	v_floor_f32_e32 v38, v38
	v_fma_f32 v37, v37, 0.15915494, -v38
	v_sin_f32_e32 v48, v37
	v_cos_f32_e32 v50, v37
	v_mul_f32_e32 v37, v131, v36
	v_mul_f32_e32 v38, 0.15915494, v37
	v_floor_f32_e32 v38, v38
	v_fma_f32 v37, v37, 0.15915494, -v38
	v_sin_f32_e32 v49, v37
	v_cos_f32_e32 v51, v37
	v_mul_f32_e32 v37, v132, v36
	v_mul_f32_e32 v38, 0.15915494, v37
	v_floor_f32_e32 v38, v38
	v_fma_f32 v37, v37, 0.15915494, -v38
	v_mul_f32_e32 v36, v133, v36
	v_sin_f32_e32 v52, v37
	v_cos_f32_e32 v54, v37
	v_mul_f32_e32 v37, 0.15915494, v36
	v_floor_f32_e32 v37, v37
	v_fma_f32 v36, v36, 0.15915494, -v37
	v_sin_f32_e32 v53, v36
	v_cos_f32_e32 v55, v36
	v_mov_b64_e32 v[36:37], s[24:25]
	v_mad_i64_i32 v[36:37], s[0:1], v35, s96, v[36:37]
	v_lshl_add_u64 v[56:57], v[150:151], 1, v[36:37]
	v_pk_mul_f32 v[36:37], v[22:23], v[40:41]
	v_pk_mul_f32 v[38:39], v[24:25], v[44:45]
	v_pk_fma_f32 v[36:37], v[30:31], v[42:43], v[36:37] neg_lo:[0,0,1] neg_hi:[0,0,1]
	v_pk_fma_f32 v[38:39], v[32:33], v[46:47], v[38:39] neg_lo:[0,0,1] neg_hi:[0,0,1]
	v_pk_mul_f32 v[36:37], v[36:37], v[34:35] op_sel_hi:[1,0]
	v_pk_mul_f32 v[38:39], v[38:39], v[34:35] op_sel_hi:[1,0]
	v_cvt_pk_bf16_f32 v36, v36, v37
	v_cvt_pk_bf16_f32 v37, v38, v39
	v_pk_mul_f32 v[38:39], v[18:19], v[48:49]
	v_pk_mul_f32 v[22:23], v[22:23], v[42:43]
	v_pk_mul_f32 v[24:25], v[24:25], v[46:47]
	v_pk_mul_f32 v[18:19], v[18:19], v[50:51]
	v_pk_fma_f32 v[22:23], v[30:31], v[40:41], v[22:23]
	v_pk_fma_f32 v[24:25], v[32:33], v[44:45], v[24:25]
	v_pk_fma_f32 v[18:19], v[26:27], v[48:49], v[18:19]
	v_pk_mul_f32 v[22:23], v[22:23], v[34:35] op_sel_hi:[1,0]
	v_pk_mul_f32 v[24:25], v[24:25], v[34:35] op_sel_hi:[1,0]
	v_pk_mul_f32 v[18:19], v[18:19], v[34:35] op_sel_hi:[1,0]
	v_cvt_pk_bf16_f32 v22, v22, v23
	v_cvt_pk_bf16_f32 v23, v24, v25
	v_cvt_pk_bf16_f32 v24, v18, v19
	v_pk_mul_f32 v[18:19], v[20:21], v[54:55]
	v_pk_mul_f32 v[58:59], v[20:21], v[52:53]
	v_pk_fma_f32 v[18:19], v[28:29], v[52:53], v[18:19]
	v_pk_fma_f32 v[38:39], v[26:27], v[50:51], v[38:39] neg_lo:[0,0,1] neg_hi:[0,0,1]
	v_pk_mul_f32 v[18:19], v[18:19], v[34:35] op_sel_hi:[1,0]
	v_pk_fma_f32 v[58:59], v[28:29], v[54:55], v[58:59] neg_lo:[0,0,1] neg_hi:[0,0,1]
	v_cvt_pk_bf16_f32 v25, v18, v19
	v_add_u32_e32 v19, 0xb0, v172
	v_ashrrev_i32_e32 v18, 31, v19
	v_lshrrev_b32_e32 v18, 20, v18
	v_add_u32_e32 v18, v19, v18
	v_ashrrev_i32_e32 v18, 12, v18
	v_lshlrev_b32_e32 v20, 13, v18
	v_mul_i32_i24_e32 v18, 0x1000, v18
	v_sub_u32_e32 v18, v19, v18
	v_pk_mul_f32 v[38:39], v[38:39], v[34:35] op_sel_hi:[1,0]
	v_pk_mul_f32 v[58:59], v[58:59], v[34:35] op_sel_hi:[1,0]
	v_add3_u32 v20, v18, s26, v20
	v_cvt_pk_bf16_f32 v38, v38, v39
	v_cvt_pk_bf16_f32 v39, v58, v59
	v_ashrrev_i32_e32 v21, 31, v20
	global_store_dwordx4 v[56:57], v[36:39], off
	global_store_dwordx4 v[56:57], v[22:25], off offset:256
	v_lshl_add_u64 v[20:21], v[20:21], 2, s[80:81]
	s_mov_b64 s[0:1], -1
	s_cbranch_vccnz .LBB0_309
	v_cmp_gt_f32_e32 vcc, s16, v83
	s_mov_b64 s[0:1], 0
	s_nop 0
	v_cndmask_b32_e32 v21, 0, v210, vcc
	v_add_f32_e32 v21, v83, v21
	v_exp_f32_e32 v21, v21
	v_cndmask_b32_e32 v18, 0, v212, vcc
	v_ldexp_f32 v18, v21, v18

; DI int grow_of(int lrow, int seg) { return (lrow / SEG) * S + seg * SEG + (lrow % SEG); }
;     DI void operator()(const f32x4 (&acc)[2][2][4][2], const Unit& u, int wr, int wc, int fr, int fq) const {
;     ...
;                 for (int m = 0; m < 4; ++m) {
;                     const int lrow = lrow0 + ai * HALF + m * 16;
;                     const float ps = (float)pos[grow_of(lrow, seg)];
;                     const float pc = (float)((lrow & 63) + 1) * lg2;
;                     const float sc = (kc == 6) ? 0.0625f * exp2f(-pc) : exp2f(pc);
;                     float o1[8], o2[8];
; #pragma unroll
;                     for (int e = 0; e < 8; ++e) {
;                         const float fe = (e < 4) ? f0[e & 3] : f1[e & 3];
;                         const float ang = ps * fe;
;                         float rev = ang * 0.15915494309189535f; rev = rev - floorf(rev);
;                         const float sn = __builtin_amdgcn_sinf(rev), cs = __builtin_amdgcn_cosf(rev);
;                         const float a = acc[ai][0][m][e >> 2][e & 3], b = acc[ai][1][m][e >> 2][e & 3];
;                         o1[e] = (a * cs - b * sn) * sc; o2[e] = (b * cs + a * sn) * sc;
;                     }
;                     bf16_t* rowp = O + (size_t)lrow * NPC + col0;
;                     u32x4 w1, w2;
;                     w1.x = cvt_pk_bf16(o1[0], o1[1]); w1.y = cvt_pk_bf16(o1[2], o1[3]); w1.z = cvt_pk_bf16(o1[4], o1[5]); w1.w = cvt_pk_bf16(o1[6], o1[7]);
;                     w2.x = cvt_pk_bf16(o2[0], o2[1]); w2.y = cvt_pk_bf16(o2[2], o2[3]); w2.z = cvt_pk_bf16(o2[4], o2[5]); w2.w = cvt_pk_bf16(o2[6], o2[7]);
;                     *(u32x4*)rowp = w1; *(u32x4*)(rowp + HALF) = w2;
;                 }
.LBB0_311:
	v_cvt_f32_i32_e32 v20, v224
	v_mul_f32_e32 v21, v134, v20
	v_mul_f32_e32 v23, 0.15915494, v21
	v_mul_f32_e32 v22, v135, v20
	v_floor_f32_e32 v23, v23
	v_mul_f32_e32 v25, 0.15915494, v22
	v_fma_f32 v21, v21, 0.15915494, -v23
	v_sin_f32_e32 v24, v21
	v_cos_f32_e32 v26, v21
	v_floor_f32_e32 v21, v25
	v_fma_f32 v21, v22, 0.15915494, -v21
	v_sin_f32_e32 v25, v21
	v_cos_f32_e32 v27, v21
	v_mul_f32_e32 v21, v136, v20
	v_mul_f32_e32 v22, 0.15915494, v21
	v_floor_f32_e32 v22, v22
	v_fma_f32 v21, v21, 0.15915494, -v22
	v_sin_f32_e32 v28, v21
	v_cos_f32_e32 v30, v21
	v_mul_f32_e32 v21, v137, v20
	v_mul_f32_e32 v22, 0.15915494, v21
	v_floor_f32_e32 v22, v22
	v_fma_f32 v21, v21, 0.15915494, -v22
	v_sin_f32_e32 v29, v21
	v_cos_f32_e32 v31, v21
	v_mul_f32_e32 v21, v130, v20
	v_mul_f32_e32 v22, 0.15915494, v21
	v_floor_f32_e32 v22, v22
	v_fma_f32 v21, v21, 0.15915494, -v22
	v_sin_f32_e32 v32, v21
	v_cos_f32_e32 v34, v21
	v_mul_f32_e32 v21, v131, v20
	v_mul_f32_e32 v22, 0.15915494, v21
	v_floor_f32_e32 v22, v22
	v_fma_f32 v21, v21, 0.15915494, -v22
	v_sin_f32_e32 v33, v21
	v_cos_f32_e32 v35, v21
	v_mul_f32_e32 v21, v132, v20
	v_mul_f32_e32 v22, 0.15915494, v21
	v_floor_f32_e32 v22, v22
	v_fma_f32 v21, v21, 0.15915494, -v22
	v_mul_f32_e32 v20, v133, v20
	v_sin_f32_e32 v36, v21
	v_cos_f32_e32 v38, v21
	v_mul_f32_e32 v21, 0.15915494, v20
	v_floor_f32_e32 v21, v21
	v_fma_f32 v20, v20, 0.15915494, -v21
	v_sin_f32_e32 v37, v20
	v_cos_f32_e32 v39, v20
	v_mov_b64_e32 v[20:21], s[24:25]
	v_mad_i64_i32 v[20:21], s[0:1], v19, s96, v[20:21]
	v_lshl_add_u64 v[40:41], v[150:151], 1, v[20:21]
	v_pk_mul_f32 v[20:21], v[6:7], v[24:25]
	v_pk_mul_f32 v[22:23], v[8:9], v[28:29]
	v_pk_fma_f32 v[20:21], v[14:15], v[26:27], v[20:21] neg_lo:[0,0,1] neg_hi:[0,0,1]
	v_pk_fma_f32 v[22:23], v[16:17], v[30:31], v[22:23] neg_lo:[0,0,1] neg_hi:[0,0,1]
	v_pk_mul_f32 v[20:21], v[20:21], v[18:19] op_sel_hi:[1,0]
	v_pk_mul_f32 v[22:23], v[22:23], v[18:19] op_sel_hi:[1,0]
	v_cvt_pk_bf16_f32 v20, v20, v21
	v_cvt_pk_bf16_f32 v21, v22, v23
	v_pk_mul_f32 v[22:23], v[2:3], v[32:33]
	v_pk_mul_f32 v[6:7], v[6:7], v[26:27]
	v_pk_mul_f32 v[8:9], v[8:9], v[30:31]
	v_pk_mul_f32 v[2:3], v[2:3], v[34:35]
	v_pk_fma_f32 v[6:7], v[14:15], v[24:25], v[6:7]
	v_pk_fma_f32 v[8:9], v[16:17], v[28:29], v[8:9]
	v_pk_fma_f32 v[2:3], v[10:11], v[32:33], v[2:3]
	v_pk_mul_f32 v[42:43], v[4:5], v[36:37]
	v_pk_mul_f32 v[6:7], v[6:7], v[18:19] op_sel_hi:[1,0]
	v_pk_mul_f32 v[8:9], v[8:9], v[18:19] op_sel_hi:[1,0]
	v_pk_mul_f32 v[2:3], v[2:3], v[18:19] op_sel_hi:[1,0]
	v_pk_fma_f32 v[22:23], v[10:11], v[34:35], v[22:23] neg_lo:[0,0,1] neg_hi:[0,0,1]
	v_pk_fma_f32 v[42:43], v[12:13], v[38:39], v[42:43] neg_lo:[0,0,1] neg_hi:[0,0,1]
	v_cvt_pk_bf16_f32 v6, v6, v7
	v_cvt_pk_bf16_f32 v7, v8, v9
	v_cvt_pk_bf16_f32 v8, v2, v3
	v_pk_mul_f32 v[2:3], v[4:5], v[38:39]
	v_pk_mul_f32 v[22:23], v[22:23], v[18:19] op_sel_hi:[1,0]
	v_pk_mul_f32 v[42:43], v[42:43], v[18:19] op_sel_hi:[1,0]
	v_pk_fma_f32 v[2:3], v[12:13], v[36:37], v[2:3]
	v_cvt_pk_bf16_f32 v22, v22, v23
	v_cvt_pk_bf16_f32 v23, v42, v43
	v_pk_mul_f32 v[2:3], v[2:3], v[18:19] op_sel_hi:[1,0]
	s_nop 0
	v_cvt_pk_bf16_f32 v9, v2, v3
	global_store_dwordx4 v[40:41], v[20:23], off
	global_store_dwordx4 v[40:41], v[6:9], off offset:256
	s_and_b64 vcc, exec, s[40:41]
	s_mov_b64 s[0:1], -1
	s_cbranch_vccnz .LBB0_230

; DI unsigned xb_ld(unsigned* p)              { return __hip_atomic_load(p, __ATOMIC_RELAXED, __HIP_MEMORY_SCOPE_AGENT); }
; DI unsigned xb_add(unsigned* p, unsigned v) { return __hip_atomic_fetch_add(p, v, __ATOMIC_RELAXED, __HIP_MEMORY_SCOPE_AGENT); }
; #define XB_SPIN(cond, bar) do { unsigned _sp = 0; while (cond) { __builtin_amdgcn_s_sleep(1); \
;     if ((++_sp & 255u) == 0u) { if (xb_ld(&(bar)[XB_TMO])) break; if (_sp > XB_SPIN_CAP) { atomicAdd(&(bar)[XB_TMO], 1u); break; } } } } while (0)
; DI void xcd_barrier(const XcdBarrier& b) {
;     ...
;     if (threadIdx.x == 0) {
;         unsigned* bar = b.bar;
;         __builtin_amdgcn_s_waitcnt(0);
;         unsigned nloc = b.st[0], nx = b.st[1];
;         if (nloc == 0u) { xcd_barrier_complete(bar, b.x, nloc, nx); b.st[0] = nloc; b.st[1] = nx; }
;         const unsigned old = xb_add(&bar[XB_XSUB(b.x)], 1u);
;         const unsigned gen = old / nloc;
;         if (old + 1u == (gen + 1u) * nloc) {
;             __builtin_amdgcn_fence(__ATOMIC_RELEASE, "agent");
;             asm volatile("s_waitcnt vmcnt(0)" ::: "memory");
;             const unsigned og = xb_add(&bar[XB_TOP], 1u);
;             const unsigned tg = og / nx;
;             if (og + 1u == (tg + 1u) * nx) xb_add(&bar[XB_TOPGEN], 1u);
;             else XB_SPIN(xb_ld(&bar[XB_TOPGEN]) == tg, bar);
;             __builtin_amdgcn_fence(__ATOMIC_ACQUIRE, "agent");
;             xb_add(&bar[XB_XGEN(b.x)], 1u);
;             asm volatile("s_waitcnt vmcnt(0)" ::: "memory");
;         } else {
;             XB_SPIN(xb_ld(&bar[XB_TOPGEN]) == gen, bar);
;             __builtin_amdgcn_fence(__ATOMIC_ACQUIRE, "agent");
;             asm volatile("s_waitcnt vmcnt(0)" ::: "memory");
;         }
.LBB0_335:
	s_or_b64 exec, exec, s[12:13]
	v_cvt_f32_u32_e32 v5, v3
	s_waitcnt vmcnt(0)
	v_readfirstlane_b32 s6, v4
	v_sub_u32_e32 v4, 0, v3
	v_rcp_iflag_f32_e32 v5, v5
	v_add_u32_e32 v6, s6, v0
	v_mul_f32_e32 v5, 0x4f7ffffe, v5
	v_cvt_u32_f32_e32 v5, v5
	v_mul_lo_u32 v0, v4, v5
	v_mul_hi_u32 v0, v5, v0
	v_add_u32_e32 v0, v5, v0
	v_mul_hi_u32 v0, v6, v0
	v_mul_lo_u32 v4, v0, v3
	v_sub_u32_e32 v4, v6, v4
	v_add_u32_e32 v5, 1, v0
	v_cmp_ge_u32_e32 vcc, v4, v3
	s_nop 1
	v_cndmask_b32_e32 v0, v0, v5, vcc
	v_sub_u32_e32 v5, v4, v3
	v_cndmask_b32_e32 v4, v4, v5, vcc
	v_add_u32_e32 v5, 1, v0
	v_cmp_ge_u32_e32 vcc, v4, v3
	v_add_u32_e32 v4, 1, v6
	s_nop 0
	v_cndmask_b32_e32 v0, v0, v5, vcc
	v_mul_lo_u32 v5, v3, v0
	v_add_u32_e32 v3, v5, v3
	v_cmp_ne_u32_e32 vcc, v4, v3
	s_and_saveexec_b64 s[12:13], vcc
	s_xor_b64 s[12:13], exec, s[12:13]
	s_cbranch_execz .LBB0_349
	v_readlane_b32 s18, v251, 2
	v_readlane_b32 s19, v251, 3
	s_waitcnt lgkmcnt(0)
	s_nop 3
	buffer_inv sc1
	global_load_dword v2, v1, s[18:19] sc1
	s_waitcnt vmcnt(0)
	v_cmp_eq_u32_e32 vcc, v2, v0
	s_and_saveexec_b64 s[40:41], vcc
	s_cbranch_execz .LBB0_348
	s_mov_b32 s6, 1
	s_mov_b64 s[42:43], 0
	s_branch .LBB0_339

; DI unsigned xb_ld(unsigned* p)              { return __hip_atomic_load(p, __ATOMIC_RELAXED, __HIP_MEMORY_SCOPE_AGENT); }
; #define XB_SPIN(cond, bar) do { unsigned _sp = 0; while (cond) { __builtin_amdgcn_s_sleep(1); \
;     if ((++_sp & 255u) == 0u) { if (xb_ld(&(bar)[XB_TMO])) break; if (_sp > XB_SPIN_CAP) { atomicAdd(&(bar)[XB_TMO], 1u); break; } } } } while (0)
; DI void xcd_barrier(const XcdBarrier& b) {
;     ...
;             XB_SPIN(xb_ld(&bar[XB_TOPGEN]) == gen, bar);
;             __builtin_amdgcn_fence(__ATOMIC_ACQUIRE, "agent");
;             asm volatile("s_waitcnt vmcnt(0)" ::: "memory");
.LBB0_348:
	s_or_b64 exec, exec, s[40:41]
	s_waitcnt vmcnt(0)
	s_waitcnt vmcnt(0)

; DI unsigned xb_ld(unsigned* p)              { return __hip_atomic_load(p, __ATOMIC_RELAXED, __HIP_MEMORY_SCOPE_AGENT); }
; DI unsigned xb_add(unsigned* p, unsigned v) { return __hip_atomic_fetch_add(p, v, __ATOMIC_RELAXED, __HIP_MEMORY_SCOPE_AGENT); }
; #define XB_SPIN(cond, bar) do { unsigned _sp = 0; while (cond) { __builtin_amdgcn_s_sleep(1); \
;     if ((++_sp & 255u) == 0u) { if (xb_ld(&(bar)[XB_TMO])) break; if (_sp > XB_SPIN_CAP) { atomicAdd(&(bar)[XB_TMO], 1u); break; } } } } while (0)
; DI void xcd_barrier(const XcdBarrier& b) {
;     ...
;     if (threadIdx.x == 0) {
;         unsigned* bar = b.bar;
;         __builtin_amdgcn_s_waitcnt(0);
;         unsigned nloc = b.st[0], nx = b.st[1];
;         if (nloc == 0u) { xcd_barrier_complete(bar, b.x, nloc, nx); b.st[0] = nloc; b.st[1] = nx; }
;         const unsigned old = xb_add(&bar[XB_XSUB(b.x)], 1u);
;         const unsigned gen = old / nloc;
;         if (old + 1u == (gen + 1u) * nloc) {
;             __builtin_amdgcn_fence(__ATOMIC_RELEASE, "agent");
;             asm volatile("s_waitcnt vmcnt(0)" ::: "memory");
;             const unsigned og = xb_add(&bar[XB_TOP], 1u);
;             const unsigned tg = og / nx;
;             if (og + 1u == (tg + 1u) * nx) xb_add(&bar[XB_TOPGEN], 1u);
;             else XB_SPIN(xb_ld(&bar[XB_TOPGEN]) == tg, bar);
;             __builtin_amdgcn_fence(__ATOMIC_ACQUIRE, "agent");
;             xb_add(&bar[XB_XGEN(b.x)], 1u);
;             asm volatile("s_waitcnt vmcnt(0)" ::: "memory");
;         } else {
;             XB_SPIN(xb_ld(&bar[XB_TOPGEN]) == gen, bar);
;             __builtin_amdgcn_fence(__ATOMIC_ACQUIRE, "agent");
;             asm volatile("s_waitcnt vmcnt(0)" ::: "memory");
;         }
.LBB0_441:
	s_or_b64 exec, exec, s[40:41]
	v_cvt_f32_u32_e32 v5, v3
	s_waitcnt vmcnt(0)
	v_readfirstlane_b32 s6, v4
	v_sub_u32_e32 v4, 0, v3
	v_rcp_iflag_f32_e32 v5, v5
	v_add_u32_e32 v6, s6, v0
	v_mul_f32_e32 v5, 0x4f7ffffe, v5
	v_cvt_u32_f32_e32 v5, v5
	v_mul_lo_u32 v0, v4, v5
	v_mul_hi_u32 v0, v5, v0
	v_add_u32_e32 v0, v5, v0
	v_mul_hi_u32 v0, v6, v0
	v_mul_lo_u32 v4, v0, v3
	v_sub_u32_e32 v4, v6, v4
	v_add_u32_e32 v5, 1, v0
	v_cmp_ge_u32_e32 vcc, v4, v3
	s_nop 1
	v_cndmask_b32_e32 v0, v0, v5, vcc
	v_sub_u32_e32 v5, v4, v3
	v_cndmask_b32_e32 v4, v4, v5, vcc
	v_add_u32_e32 v5, 1, v0
	v_cmp_ge_u32_e32 vcc, v4, v3
	v_add_u32_e32 v4, 1, v6
	s_nop 0
	v_cndmask_b32_e32 v0, v0, v5, vcc
	v_mul_lo_u32 v5, v3, v0
	v_add_u32_e32 v3, v5, v3
	v_cmp_ne_u32_e32 vcc, v4, v3
	s_and_saveexec_b64 s[22:23], vcc
	s_xor_b64 s[40:41], exec, s[22:23]
	s_cbranch_execz .LBB0_455
	v_readlane_b32 s18, v251, 2
	v_readlane_b32 s19, v251, 3
	s_waitcnt lgkmcnt(0)
	s_nop 3
	buffer_inv sc1
	global_load_dword v2, v1, s[18:19] sc1
	s_waitcnt vmcnt(0)
	v_cmp_eq_u32_e32 vcc, v2, v0
	s_and_saveexec_b64 s[42:43], vcc
	s_cbranch_execz .LBB0_454
	s_mov_b32 s6, 1
	s_mov_b64 s[44:45], 0
	s_branch .LBB0_445

; DI unsigned xb_ld(unsigned* p)              { return __hip_atomic_load(p, __ATOMIC_RELAXED, __HIP_MEMORY_SCOPE_AGENT); }
; DI unsigned xb_add(unsigned* p, unsigned v) { return __hip_atomic_fetch_add(p, v, __ATOMIC_RELAXED, __HIP_MEMORY_SCOPE_AGENT); }
; #define XB_SPIN(cond, bar) do { unsigned _sp = 0; while (cond) { __builtin_amdgcn_s_sleep(1); \
;     if ((++_sp & 255u) == 0u) { if (xb_ld(&(bar)[XB_TMO])) break; if (_sp > XB_SPIN_CAP) { atomicAdd(&(bar)[XB_TMO], 1u); break; } } } } while (0)
; DI void xcd_barrier(const XcdBarrier& b) {
;     ...
;     if (threadIdx.x == 0) {
;         unsigned* bar = b.bar;
;         __builtin_amdgcn_s_waitcnt(0);
;         unsigned nloc = b.st[0], nx = b.st[1];
;         if (nloc == 0u) { xcd_barrier_complete(bar, b.x, nloc, nx); b.st[0] = nloc; b.st[1] = nx; }
;         const unsigned old = xb_add(&bar[XB_XSUB(b.x)], 1u);
;         const unsigned gen = old / nloc;
;         if (old + 1u == (gen + 1u) * nloc) {
;             __builtin_amdgcn_fence(__ATOMIC_RELEASE, "agent");
;             asm volatile("s_waitcnt vmcnt(0)" ::: "memory");
;             const unsigned og = xb_add(&bar[XB_TOP], 1u);
;             const unsigned tg = og / nx;
;             if (og + 1u == (tg + 1u) * nx) xb_add(&bar[XB_TOPGEN], 1u);
;             else XB_SPIN(xb_ld(&bar[XB_TOPGEN]) == tg, bar);
;             __builtin_amdgcn_fence(__ATOMIC_ACQUIRE, "agent");
;             xb_add(&bar[XB_XGEN(b.x)], 1u);
;             asm volatile("s_waitcnt vmcnt(0)" ::: "memory");
;         } else {
;             XB_SPIN(xb_ld(&bar[XB_TOPGEN]) == gen, bar);
;             __builtin_amdgcn_fence(__ATOMIC_ACQUIRE, "agent");
;             asm volatile("s_waitcnt vmcnt(0)" ::: "memory");
;         }
.LBB0_522:
	s_or_b64 exec, exec, s[40:41]
	v_cvt_f32_u32_e32 v5, v3
	s_waitcnt vmcnt(0)
	v_readfirstlane_b32 s6, v4
	v_sub_u32_e32 v4, 0, v3
	v_rcp_iflag_f32_e32 v5, v5
	v_add_u32_e32 v6, s6, v0
	v_mul_f32_e32 v5, 0x4f7ffffe, v5
	v_cvt_u32_f32_e32 v5, v5
	v_mul_lo_u32 v0, v4, v5
	v_mul_hi_u32 v0, v5, v0
	v_add_u32_e32 v0, v5, v0
	v_mul_hi_u32 v0, v6, v0
	v_mul_lo_u32 v4, v0, v3
	v_sub_u32_e32 v4, v6, v4
	v_add_u32_e32 v5, 1, v0
	v_cmp_ge_u32_e32 vcc, v4, v3
	s_nop 1
	v_cndmask_b32_e32 v0, v0, v5, vcc
	v_sub_u32_e32 v5, v4, v3
	v_cndmask_b32_e32 v4, v4, v5, vcc
	v_add_u32_e32 v5, 1, v0
	v_cmp_ge_u32_e32 vcc, v4, v3
	v_add_u32_e32 v4, 1, v6
	s_nop 0
	v_cndmask_b32_e32 v0, v0, v5, vcc
	v_mul_lo_u32 v5, v3, v0
	v_add_u32_e32 v3, v5, v3
	v_cmp_ne_u32_e32 vcc, v4, v3
	s_and_saveexec_b64 s[8:9], vcc
	s_xor_b64 s[40:41], exec, s[8:9]
	s_cbranch_execz .LBB0_536
	v_readlane_b32 s8, v251, 2
	v_readlane_b32 s9, v251, 3
	s_waitcnt lgkmcnt(0)
	s_nop 3
	buffer_inv sc1
	global_load_dword v2, v1, s[8:9] sc1
	s_waitcnt vmcnt(0)
	v_cmp_eq_u32_e32 vcc, v2, v0
	s_and_saveexec_b64 s[42:43], vcc
	s_cbranch_execz .LBB0_535
	s_mov_b32 s6, 1
	s_mov_b64 s[44:45], 0
	s_branch .LBB0_526
